# v2 plus: in-proj K-loop weight stage loads nt
# baseline (speedup 1.0000x reference)
.LBB0_99:
	s_and_b64 vcc, exec, s[6:7]
	s_cbranch_vccz .LBB0_132
	v_ashrrev_i32_e32 v3, 31, v2
	v_lshrrev_b32_e32 v3, 26, v3
	v_add_u32_e32 v3, v2, v3
	v_ashrrev_i32_e32 v4, 6, v3
	v_bfe_i32 v3, v2, 27, 1
	v_lshlrev_b32_e32 v5, 4, v2
	v_lshrrev_b32_e32 v3, 22, v3
	v_add_u32_e32 v3, v5, v3
	v_and_b32_e32 v3, 0xfffffc00, v3
	v_sub_u32_e32 v3, v5, v3
	v_lshrrev_b32_e32 v6, 4, v3
	v_bitop3_b32 v6, v6, v3, 32 bitop3:0x6c
	v_ashrrev_i32_e32 v7, 31, v6
	v_lshrrev_b32_e32 v7, 26, v7
	v_add_u32_e32 v7, v6, v7
	v_ashrrev_i32_e32 v8, 6, v7
	v_and_b32_e32 v7, 0xc0, v7
	v_sub_u32_e32 v6, v6, v7
	v_mov_b32_e32 v7, 1
	v_lshlrev_b32_e32 v3, 3, v4
	v_lshlrev_b32_e32 v4, 5, v4
	v_ashrrev_i16_sdwa v6, v7, sext(v6) dst_sel:DWORD dst_unused:UNUSED_PAD src0_sel:DWORD src1_sel:BYTE_0
	v_and_b32_e32 v3, -16, v3
	v_and_b32_e32 v4, 32, v4
	v_bfe_i32 v6, v6, 0, 16
	v_add_u32_e32 v5, 0x2000, v5
	v_add_u32_e32 v3, v8, v3
	v_add_lshl_u32 v4, v4, v6, 1
	v_ashrrev_i32_e32 v6, 31, v5
	v_lshlrev_b32_e32 v9, 1, v3
	v_lshrrev_b32_e32 v10, 2, v3
	v_and_b32_e32 v8, 3, v8
	s_mov_b32 s7, 0x1fffe0
	v_lshrrev_b32_e32 v6, 22, v6
	v_and_b32_e32 v9, 24, v9
	v_and_b32_e32 v10, 4, v10
	v_and_or_b32 v8, v3, s7, v8
	v_add_u32_e32 v6, v5, v6
	v_or3_b32 v8, v8, v10, v9
	v_ashrrev_i32_e32 v6, 10, v6
	v_lshl_add_u32 v154, v8, 11, v4
	v_mul_i32_i24_e32 v8, 0x400, v6
	v_sub_u32_e32 v5, v5, v8
	v_lshrrev_b32_e32 v8, 4, v5
	v_bitop3_b32 v8, v8, v5, 32 bitop3:0x6c
	v_ashrrev_i32_e32 v9, 31, v8
	v_lshrrev_b32_e32 v9, 26, v9
	v_lshlrev_b32_e32 v5, 3, v6
	v_add_u32_e32 v9, v8, v9
	s_add_u32 s8, s2, 0x200000
	v_and_b32_e32 v5, -16, v5
	v_ashrrev_i32_e32 v10, 6, v9
	s_addc_u32 s6, s3, 0
	v_add_u32_e32 v5, v10, v5
	v_and_b32_e32 v10, 3, v10
	s_ashr_i32 s20, s18, 31
	v_and_or_b32 v10, v5, s7, v10
	s_lshr_b32 s7, s20, 29
	s_add_i32 s7, s18, s7
	s_ashr_i32 s34, s41, 6
	s_ashr_i32 s12, s7, 3
	s_and_b32 s7, s7, -8
	s_and_b32 s9, s6, 0xffff
	s_lshl_b32 s6, s34, 10
	s_sub_i32 s7, s18, s7
	s_cmp_lt_i32 s7, 0
	s_movk_i32 s13, 0x61
	s_cselect_b32 s13, s13, 0x60
	s_mul_i32 s7, s7, s13
	s_add_i32 s7, s7, s12
	s_mul_hi_i32 s12, s7, 0x2aaaaaab
	s_lshr_b32 s13, s12, 31
	s_ashr_i32 s26, s12, 4
	s_add_i32 s26, s26, s13
	s_mul_i32 s12, s26, 0x60
	s_sub_i32 s27, s7, s12
	s_bfe_i32 s7, s27, 0x80000
	s_bfe_u32 s7, s7, 0x3000c
	v_and_b32_e32 v9, 0xc0, v9
	s_add_i32 s7, s27, s7
	v_sub_u32_e32 v8, v8, v9
	s_bfe_i32 s7, s7, 0x80000
	v_lshlrev_b32_e32 v6, 5, v6
	v_ashrrev_i16_sdwa v7, v7, sext(v8) dst_sel:DWORD dst_unused:UNUSED_PAD src0_sel:DWORD src1_sel:BYTE_0
	v_lshlrev_b32_e32 v8, 1, v5
	v_lshrrev_b32_e32 v9, 2, v5
	s_sext_i32_i16 s28, s7
	v_and_b32_e32 v6, 32, v6
	v_bfe_i32 v7, v7, 0, 16
	v_and_b32_e32 v8, 24, v8
	v_and_b32_e32 v9, 4, v9
	s_ashr_i32 s46, s28, 3
	s_add_i32 s21, s6, 0
	v_or3_b32 v8, v10, v9, v8
	v_add_lshl_u32 v6, v6, v7, 1
	s_mov_b32 s11, 0x20000
	s_mov_b32 s10, -1
	s_lshl_b32 s53, s46, 19
	s_add_i32 s22, s21, 0x10000
	s_mov_b32 m0, s22
	s_nop 0
	buffer_load_dwordx4 v154, s[8:11], s53 offen nt lds
	v_lshl_add_u32 v155, v8, 11, v6
	s_add_i32 s23, s21, 0x12000
	s_mov_b32 m0, s23
	s_nop 0
	buffer_load_dwordx4 v155, s[8:11], s53 offen nt lds
	s_add_i32 s24, s21, 0x14000
	s_or_b32 s6, s53, 0x40000
	s_mov_b32 m0, s24
	s_nop 0
	buffer_load_dwordx4 v154, s[8:11], s6 offen nt lds
	s_add_i32 s25, s21, 0x16000
	s_mov_b32 m0, s25
	s_nop 0
	buffer_load_dwordx4 v155, s[8:11], s6 offen nt lds
	v_cmp_eq_u32_e32 vcc, 0, v0
	s_and_saveexec_b64 s[6:7], vcc
	s_cbranch_execz .LBB0_113
	v_mov_b32_e32 v7, 0
	global_load_dword v8, v7, s[4:5] sc1
	s_waitcnt vmcnt(0)
	v_cmp_lt_u32_e32 vcc, 3, v8
	s_cbranch_vccnz .LBB0_112
	s_mov_b32 s29, 1
	s_branch .LBB0_104

.LBB0_115:
	s_add_u32 s31, s2, 0x5000000
	v_lshrrev_b32_e32 v4, 1, v2
	s_addc_u32 s33, s3, 0
	v_and_b32_e32 v4, 24, v4
	s_add_u32 s2, s2, 0xdc00000
	v_and_b32_e32 v3, 15, v2
	v_lshlrev_b32_e32 v5, 1, v4
	v_lshlrev_b32_e32 v2, 2, v2
	s_addc_u32 s3, s3, 0
	v_lshl_or_b32 v130, s4, 6, v3
	v_lshl_or_b32 v3, v3, 6, v5
	s_lshl_b32 s4, s4, 13
	v_and_b32_e32 v2, 32, v2
	v_bitop3_b32 v5, v3, s4, v2 bitop3:0xde
	s_lshl_b32 s4, s34, 5
	s_and_b32 s4, s4, 0x60
	s_lshl_b32 s5, s4, 7
	v_bitop3_b32 v6, v3, s5, v2 bitop3:0xde
	s_waitcnt vmcnt(2)
	s_barrier
	s_add_i32 s34, s21, 0x18000
	s_or_b32 s5, s53, 0x80
	s_mov_b32 m0, s34
	s_nop 0
	buffer_load_dwordx4 v154, s[8:11], s5 offen nt lds
	s_add_i32 s35, s21, 0x1a000
	s_mov_b32 m0, s35
	s_nop 0
	buffer_load_dwordx4 v155, s[8:11], s5 offen nt lds
	s_add_i32 s36, s21, 0x8000
	s_or_b32 s5, s52, 0x80
	s_mov_b32 m0, s36
	s_nop 0
	buffer_load_dwordx4 v156, s[12:15], s5 offen lds
	v_or_b32_e32 v2, 16, v130
	s_add_i32 s37, s21, 0xa000
	s_mov_b32 m0, s37
	s_nop 0
	buffer_load_dwordx4 v157, s[12:15], s5 offen lds
	v_ashrrev_i32_e32 v3, 31, v2
	s_add_i32 s38, s21, 0x1c000
	s_or_b32 s5, s53, 0x40080
	s_mov_b32 m0, s38
	s_nop 0
	buffer_load_dwordx4 v154, s[8:11], s5 offen nt lds
	v_ashrrev_i32_e32 v131, 31, v130
	v_lshlrev_b64 v[134:135], 11, v[2:3]
	v_or_b32_e32 v2, 32, v130
	s_add_i32 s39, s21, 0x1e000
	s_mov_b32 m0, s39
	s_nop 0
	buffer_load_dwordx4 v155, s[8:11], s5 offen nt lds
	v_or_b32_e32 v158, s4, v4
	v_lshlrev_b64 v[132:133], 11, v[130:131]
	v_ashrrev_i32_e32 v3, 31, v2
	s_mov_b64 s[4:5], 0x40000
	v_lshlrev_b64 v[136:137], 11, v[2:3]
	v_or_b32_e32 v2, 48, v130
	v_lshl_add_u64 v[140:141], v[132:133], 0, s[4:5]
	s_mov_b64 s[4:5], 0x48000
	s_waitcnt vmcnt(6)
	s_add_i32 s40, s21, 0xc000
	v_ashrrev_i32_e32 v3, 31, v2
	v_lshl_add_u64 v[142:143], v[132:133], 0, s[4:5]
	s_mov_b64 s[4:5], 0x50000
	s_cmpk_lt_u32 s41, 0x100
	v_lshlrev_b64 v[138:139], 11, v[2:3]
	v_lshl_add_u64 v[144:145], v[132:133], 0, s[4:5]
	s_mov_b64 s[4:5], 0x58000
	v_add_u32_e32 v2, 0, v6
	v_or_b32_e32 v159, 0xfffffe00, v158
	s_cselect_b64 s[6:7], -1, 0
	v_lshl_add_u64 v[146:147], v[132:133], 0, s[4:5]
	s_add_i32 s41, s21, 0xe000
	s_ashr_i32 s42, s19, 31
	v_mov_b64_e32 v[148:149], 0x300
	v_mov_b64_e32 v[150:151], 0x2ff
	s_movk_i32 s43, 0x61
	v_add_u32_e32 v131, 0x10000, v2
	v_add_u32_e32 v160, 0x14000, v2
	v_add_u32_e32 v161, 0, v5
	v_add_u32_e32 v162, 0x18000, v2
	v_add_u32_e32 v163, 0x1c000, v2
	v_mov_b32_e32 v153, 0
	s_mov_b32 s44, 0x48000
	s_mov_b32 s45, 0x50000
	s_barrier
	s_branch .LBB0_118

.LBB0_121:
	ds_read_b128 v[164:167], v131
	ds_read_b128 v[168:171], v131 offset:1024
	ds_read_b128 v[172:175], v131 offset:2048
	ds_read_b128 v[176:179], v131 offset:3072
	ds_read_b128 v[180:183], v160
	ds_read_b128 v[184:187], v160 offset:1024
	ds_read_b128 v[188:191], v160 offset:2048
	ds_read_b128 v[192:195], v160 offset:3072
	s_add_i32 s55, s52, 0xfffc0080
	s_cmp_eq_u32 s54, 12
	s_cselect_b32 s57, s16, s55
	s_cselect_b32 s56, s17, s53
	s_or_b32 s55, s57, 0x80
	ds_read_b128 v[196:199], v161
	ds_read_b128 v[200:203], v161 offset:1024
	ds_read_b128 v[204:207], v161 offset:2048
	ds_read_b128 v[208:211], v161 offset:3072
	ds_read_b128 v[212:215], v161 offset:4096
	ds_read_b128 v[216:219], v161 offset:5120
	ds_read_b128 v[220:223], v161 offset:6144
	ds_read_b128 v[224:227], v161 offset:7168
	s_mov_b32 m0, s40
	s_nop 0
	buffer_load_dwordx4 v156, s[12:15], s52 offen lds
	s_nop 0
	s_mov_b32 m0, s41
	s_nop 0
	buffer_load_dwordx4 v157, s[12:15], s52 offen lds
	s_waitcnt vmcnt(8)
	s_waitcnt lgkmcnt(0)
	s_barrier
	s_setprio 1
	s_waitcnt lgkmcnt(7)
	v_mfma_f32_16x16x32_bf16 v[126:129], v[164:167], v[196:199], v[126:129]
	v_mfma_f32_16x16x32_bf16 v[122:125], v[172:175], v[196:199], v[122:125]
	s_waitcnt lgkmcnt(5)
	v_mfma_f32_16x16x32_bf16 v[118:121], v[164:167], v[204:207], v[118:121]
	v_mfma_f32_16x16x32_bf16 v[110:113], v[172:175], v[204:207], v[110:113]
	s_waitcnt lgkmcnt(3)
	v_mfma_f32_16x16x32_bf16 v[102:105], v[164:167], v[212:215], v[102:105]
	v_mfma_f32_16x16x32_bf16 v[94:97], v[172:175], v[212:215], v[94:97]
	s_waitcnt lgkmcnt(1)
	v_mfma_f32_16x16x32_bf16 v[86:89], v[164:167], v[220:223], v[86:89]
	v_mfma_f32_16x16x32_bf16 v[78:81], v[172:175], v[220:223], v[78:81]
	v_mfma_f32_16x16x32_bf16 v[126:129], v[168:171], v[200:203], v[126:129]
	v_mfma_f32_16x16x32_bf16 v[122:125], v[176:179], v[200:203], v[122:125]
	v_mfma_f32_16x16x32_bf16 v[118:121], v[168:171], v[208:211], v[118:121]
	v_mfma_f32_16x16x32_bf16 v[110:113], v[176:179], v[208:211], v[110:113]
	v_mfma_f32_16x16x32_bf16 v[102:105], v[168:171], v[216:219], v[102:105]
	v_mfma_f32_16x16x32_bf16 v[94:97], v[176:179], v[216:219], v[94:97]
	s_waitcnt lgkmcnt(0)
	v_mfma_f32_16x16x32_bf16 v[86:89], v[168:171], v[224:227], v[86:89]
	v_mfma_f32_16x16x32_bf16 v[78:81], v[176:179], v[224:227], v[78:81]
	s_setprio 0
	s_setprio 1
	v_mfma_f32_16x16x32_bf16 v[114:117], v[180:183], v[196:199], v[114:117]
	v_mfma_f32_16x16x32_bf16 v[106:109], v[188:191], v[196:199], v[106:109]
	v_mfma_f32_16x16x32_bf16 v[98:101], v[180:183], v[204:207], v[98:101]
	v_mfma_f32_16x16x32_bf16 v[90:93], v[188:191], v[204:207], v[90:93]
	v_mfma_f32_16x16x32_bf16 v[82:85], v[180:183], v[212:215], v[82:85]
	v_mfma_f32_16x16x32_bf16 v[74:77], v[188:191], v[212:215], v[74:77]
	v_mfma_f32_16x16x32_bf16 v[70:73], v[180:183], v[220:223], v[70:73]
	v_mfma_f32_16x16x32_bf16 v[66:69], v[188:191], v[220:223], v[66:69]
	v_mfma_f32_16x16x32_bf16 v[114:117], v[184:187], v[200:203], v[114:117]
	v_mfma_f32_16x16x32_bf16 v[106:109], v[192:195], v[200:203], v[106:109]
	v_mfma_f32_16x16x32_bf16 v[98:101], v[184:187], v[208:211], v[98:101]
	v_mfma_f32_16x16x32_bf16 v[90:93], v[192:195], v[208:211], v[90:93]
	v_mfma_f32_16x16x32_bf16 v[82:85], v[184:187], v[216:219], v[82:85]
	v_mfma_f32_16x16x32_bf16 v[74:77], v[192:195], v[216:219], v[74:77]
	v_mfma_f32_16x16x32_bf16 v[70:73], v[184:187], v[224:227], v[70:73]
	v_mfma_f32_16x16x32_bf16 v[66:69], v[192:195], v[224:227], v[66:69]
	s_setprio 0
	s_barrier
	ds_read_b128 v[196:199], v161 offset:16384
	ds_read_b128 v[200:203], v161 offset:17408
	ds_read_b128 v[204:207], v161 offset:18432
	ds_read_b128 v[208:211], v161 offset:19456
	ds_read_b128 v[212:215], v161 offset:20480
	ds_read_b128 v[216:219], v161 offset:21504
	ds_read_b128 v[220:223], v161 offset:22528
	ds_read_b128 v[224:227], v161 offset:23552
	s_mov_b32 m0, s22
	s_nop 0
	buffer_load_dwordx4 v154, s[8:11], s56 offen nt lds
	s_add_i32 s58, s56, 0x40000
	s_mov_b32 m0, s23
	s_nop 0
	buffer_load_dwordx4 v155, s[8:11], s56 offen nt lds
	s_nop 0
	s_mov_b32 m0, s24
	s_nop 0
	buffer_load_dwordx4 v154, s[8:11], s58 offen nt lds
	s_nop 0
	s_mov_b32 m0, s25
	s_nop 0
	buffer_load_dwordx4 v155, s[8:11], s58 offen nt lds
	s_nop 0
	s_mov_b32 m0, s21
	s_nop 0
	buffer_load_dwordx4 v156, s[12:15], s57 offen lds
	s_nop 0
	s_mov_b32 m0, s27
	s_nop 0
	buffer_load_dwordx4 v157, s[12:15], s57 offen lds
	s_waitcnt vmcnt(8)
	s_waitcnt lgkmcnt(0)
	s_barrier
	s_setprio 1
	s_waitcnt lgkmcnt(7)
	v_mfma_f32_16x16x32_bf16 v[62:65], v[164:167], v[196:199], v[62:65]
	v_mfma_f32_16x16x32_bf16 v[58:61], v[172:175], v[196:199], v[58:61]
	s_waitcnt lgkmcnt(5)
	v_mfma_f32_16x16x32_bf16 v[54:57], v[164:167], v[204:207], v[54:57]
	v_mfma_f32_16x16x32_bf16 v[46:49], v[172:175], v[204:207], v[46:49]
	s_waitcnt lgkmcnt(3)
	v_mfma_f32_16x16x32_bf16 v[38:41], v[164:167], v[212:215], v[38:41]
	v_mfma_f32_16x16x32_bf16 v[30:33], v[172:175], v[212:215], v[30:33]
	s_waitcnt lgkmcnt(1)
	v_mfma_f32_16x16x32_bf16 v[22:25], v[164:167], v[220:223], v[22:25]
	v_mfma_f32_16x16x32_bf16 v[14:17], v[172:175], v[220:223], v[14:17]
	v_mfma_f32_16x16x32_bf16 v[62:65], v[168:171], v[200:203], v[62:65]
	v_mfma_f32_16x16x32_bf16 v[58:61], v[176:179], v[200:203], v[58:61]
	v_mfma_f32_16x16x32_bf16 v[54:57], v[168:171], v[208:211], v[54:57]
	v_mfma_f32_16x16x32_bf16 v[46:49], v[176:179], v[208:211], v[46:49]
	v_mfma_f32_16x16x32_bf16 v[38:41], v[168:171], v[216:219], v[38:41]
	v_mfma_f32_16x16x32_bf16 v[30:33], v[176:179], v[216:219], v[30:33]
	s_waitcnt lgkmcnt(0)
	v_mfma_f32_16x16x32_bf16 v[22:25], v[168:171], v[224:227], v[22:25]
	v_mfma_f32_16x16x32_bf16 v[14:17], v[176:179], v[224:227], v[14:17]
	s_setprio 0
	s_setprio 1
	v_mfma_f32_16x16x32_bf16 v[50:53], v[180:183], v[196:199], v[50:53]
	v_mfma_f32_16x16x32_bf16 v[42:45], v[188:191], v[196:199], v[42:45]
	v_mfma_f32_16x16x32_bf16 v[34:37], v[180:183], v[204:207], v[34:37]
	v_mfma_f32_16x16x32_bf16 v[26:29], v[188:191], v[204:207], v[26:29]
	v_mfma_f32_16x16x32_bf16 v[18:21], v[180:183], v[212:215], v[18:21]
	v_mfma_f32_16x16x32_bf16 v[10:13], v[188:191], v[212:215], v[10:13]
	v_mfma_f32_16x16x32_bf16 v[6:9], v[180:183], v[220:223], v[6:9]
	v_mfma_f32_16x16x32_bf16 v[2:5], v[188:191], v[220:223], v[2:5]
	v_mfma_f32_16x16x32_bf16 v[50:53], v[184:187], v[200:203], v[50:53]
	v_mfma_f32_16x16x32_bf16 v[42:45], v[192:195], v[200:203], v[42:45]
	v_mfma_f32_16x16x32_bf16 v[34:37], v[184:187], v[208:211], v[34:37]
	v_mfma_f32_16x16x32_bf16 v[26:29], v[192:195], v[208:211], v[26:29]
	v_mfma_f32_16x16x32_bf16 v[18:21], v[184:187], v[216:219], v[18:21]
	v_mfma_f32_16x16x32_bf16 v[10:13], v[192:195], v[216:219], v[10:13]
	v_mfma_f32_16x16x32_bf16 v[6:9], v[184:187], v[224:227], v[6:9]
	v_mfma_f32_16x16x32_bf16 v[2:5], v[192:195], v[224:227], v[2:5]
	s_setprio 0
	s_barrier
	ds_read_b128 v[164:167], v162
	ds_read_b128 v[168:171], v162 offset:1024
	ds_read_b128 v[172:175], v162 offset:2048
	ds_read_b128 v[176:179], v162 offset:3072
	ds_read_b128 v[180:183], v163
	ds_read_b128 v[184:187], v163 offset:1024
	ds_read_b128 v[188:191], v163 offset:2048
	ds_read_b128 v[192:195], v163 offset:3072
	ds_read_b128 v[196:199], v161 offset:32768
	ds_read_b128 v[200:203], v161 offset:33792
	ds_read_b128 v[204:207], v161 offset:34816
	ds_read_b128 v[208:211], v161 offset:35840
	ds_read_b128 v[212:215], v161 offset:36864
	ds_read_b128 v[216:219], v161 offset:37888
	ds_read_b128 v[220:223], v161 offset:38912
	ds_read_b128 v[224:227], v161 offset:39936
	s_add_i32 s57, s57, 0x40000
	s_mov_b32 m0, s28
	s_nop 0
	buffer_load_dwordx4 v156, s[12:15], s57 offen lds
	s_nop 0
	s_mov_b32 m0, s30
	s_nop 0
	buffer_load_dwordx4 v157, s[12:15], s57 offen lds
	s_waitcnt vmcnt(8)
	s_waitcnt lgkmcnt(0)
	s_barrier
	s_setprio 1
	s_waitcnt lgkmcnt(7)
	v_mfma_f32_16x16x32_bf16 v[126:129], v[164:167], v[196:199], v[126:129]
	v_mfma_f32_16x16x32_bf16 v[122:125], v[172:175], v[196:199], v[122:125]
	s_waitcnt lgkmcnt(5)
	v_mfma_f32_16x16x32_bf16 v[118:121], v[164:167], v[204:207], v[118:121]
	v_mfma_f32_16x16x32_bf16 v[110:113], v[172:175], v[204:207], v[110:113]
	s_waitcnt lgkmcnt(3)
	v_mfma_f32_16x16x32_bf16 v[102:105], v[164:167], v[212:215], v[102:105]
	v_mfma_f32_16x16x32_bf16 v[94:97], v[172:175], v[212:215], v[94:97]
	s_waitcnt lgkmcnt(1)
	v_mfma_f32_16x16x32_bf16 v[86:89], v[164:167], v[220:223], v[86:89]
	v_mfma_f32_16x16x32_bf16 v[78:81], v[172:175], v[220:223], v[78:81]
	v_mfma_f32_16x16x32_bf16 v[126:129], v[168:171], v[200:203], v[126:129]
	v_mfma_f32_16x16x32_bf16 v[122:125], v[176:179], v[200:203], v[122:125]
	v_mfma_f32_16x16x32_bf16 v[118:121], v[168:171], v[208:211], v[118:121]
	v_mfma_f32_16x16x32_bf16 v[110:113], v[176:179], v[208:211], v[110:113]
	v_mfma_f32_16x16x32_bf16 v[102:105], v[168:171], v[216:219], v[102:105]
	v_mfma_f32_16x16x32_bf16 v[94:97], v[176:179], v[216:219], v[94:97]
	s_waitcnt lgkmcnt(0)
	v_mfma_f32_16x16x32_bf16 v[86:89], v[168:171], v[224:227], v[86:89]
	v_mfma_f32_16x16x32_bf16 v[78:81], v[176:179], v[224:227], v[78:81]
	s_setprio 0
	s_setprio 1
	v_mfma_f32_16x16x32_bf16 v[114:117], v[180:183], v[196:199], v[114:117]
	v_mfma_f32_16x16x32_bf16 v[106:109], v[188:191], v[196:199], v[106:109]
	v_mfma_f32_16x16x32_bf16 v[98:101], v[180:183], v[204:207], v[98:101]
	v_mfma_f32_16x16x32_bf16 v[90:93], v[188:191], v[204:207], v[90:93]
	v_mfma_f32_16x16x32_bf16 v[82:85], v[180:183], v[212:215], v[82:85]
	v_mfma_f32_16x16x32_bf16 v[74:77], v[188:191], v[212:215], v[74:77]
	v_mfma_f32_16x16x32_bf16 v[70:73], v[180:183], v[220:223], v[70:73]
	v_mfma_f32_16x16x32_bf16 v[66:69], v[188:191], v[220:223], v[66:69]
	v_mfma_f32_16x16x32_bf16 v[114:117], v[184:187], v[200:203], v[114:117]
	v_mfma_f32_16x16x32_bf16 v[106:109], v[192:195], v[200:203], v[106:109]
	v_mfma_f32_16x16x32_bf16 v[98:101], v[184:187], v[208:211], v[98:101]
	v_mfma_f32_16x16x32_bf16 v[90:93], v[192:195], v[208:211], v[90:93]
	v_mfma_f32_16x16x32_bf16 v[82:85], v[184:187], v[216:219], v[82:85]
	v_mfma_f32_16x16x32_bf16 v[74:77], v[192:195], v[216:219], v[74:77]
	v_mfma_f32_16x16x32_bf16 v[70:73], v[184:187], v[224:227], v[70:73]
	v_mfma_f32_16x16x32_bf16 v[66:69], v[192:195], v[224:227], v[66:69]
	s_setprio 0
	s_barrier
	ds_read_b128 v[196:199], v161 offset:49152
	ds_read_b128 v[200:203], v161 offset:50176
	ds_read_b128 v[204:207], v161 offset:51200
	ds_read_b128 v[208:211], v161 offset:52224
	ds_read_b128 v[212:215], v161 offset:53248
	ds_read_b128 v[216:219], v161 offset:54272
	ds_read_b128 v[220:223], v161 offset:55296
	ds_read_b128 v[224:227], v161 offset:56320
	s_or_b32 s57, s56, 0x80
	s_mov_b32 m0, s34
	s_nop 0
	buffer_load_dwordx4 v154, s[8:11], s57 offen nt lds
	s_add_i32 s56, s56, 0x40080
	s_mov_b32 m0, s35
	s_nop 0
	buffer_load_dwordx4 v155, s[8:11], s57 offen nt lds
	s_nop 0
	s_mov_b32 m0, s38
	s_nop 0
	buffer_load_dwordx4 v154, s[8:11], s56 offen nt lds
	s_nop 0
	s_mov_b32 m0, s39
	s_nop 0
	buffer_load_dwordx4 v155, s[8:11], s56 offen nt lds
	s_nop 0
	s_mov_b32 m0, s36
	s_nop 0
	buffer_load_dwordx4 v156, s[12:15], s55 offen lds
	s_nop 0
	s_mov_b32 m0, s37
	s_nop 0
	buffer_load_dwordx4 v157, s[12:15], s55 offen lds
	s_waitcnt vmcnt(8)
	s_waitcnt lgkmcnt(0)
	s_barrier
	s_setprio 1
	s_waitcnt lgkmcnt(7)
	v_mfma_f32_16x16x32_bf16 v[62:65], v[164:167], v[196:199], v[62:65]
	v_mfma_f32_16x16x32_bf16 v[58:61], v[172:175], v[196:199], v[58:61]
	s_waitcnt lgkmcnt(5)
	v_mfma_f32_16x16x32_bf16 v[54:57], v[164:167], v[204:207], v[54:57]
	v_mfma_f32_16x16x32_bf16 v[46:49], v[172:175], v[204:207], v[46:49]
	s_waitcnt lgkmcnt(3)
	v_mfma_f32_16x16x32_bf16 v[38:41], v[164:167], v[212:215], v[38:41]
	v_mfma_f32_16x16x32_bf16 v[30:33], v[172:175], v[212:215], v[30:33]
	s_waitcnt lgkmcnt(1)
	v_mfma_f32_16x16x32_bf16 v[22:25], v[164:167], v[220:223], v[22:25]
	v_mfma_f32_16x16x32_bf16 v[14:17], v[172:175], v[220:223], v[14:17]
	v_mfma_f32_16x16x32_bf16 v[62:65], v[168:171], v[200:203], v[62:65]
	v_mfma_f32_16x16x32_bf16 v[58:61], v[176:179], v[200:203], v[58:61]
	v_mfma_f32_16x16x32_bf16 v[54:57], v[168:171], v[208:211], v[54:57]
	v_mfma_f32_16x16x32_bf16 v[46:49], v[176:179], v[208:211], v[46:49]
	v_mfma_f32_16x16x32_bf16 v[38:41], v[168:171], v[216:219], v[38:41]
	v_mfma_f32_16x16x32_bf16 v[30:33], v[176:179], v[216:219], v[30:33]
	s_waitcnt lgkmcnt(0)
	v_mfma_f32_16x16x32_bf16 v[22:25], v[168:171], v[224:227], v[22:25]
	v_mfma_f32_16x16x32_bf16 v[14:17], v[176:179], v[224:227], v[14:17]
	s_setprio 0
	s_setprio 1
	v_mfma_f32_16x16x32_bf16 v[50:53], v[180:183], v[196:199], v[50:53]
	v_mfma_f32_16x16x32_bf16 v[42:45], v[188:191], v[196:199], v[42:45]
	v_mfma_f32_16x16x32_bf16 v[34:37], v[180:183], v[204:207], v[34:37]
	v_mfma_f32_16x16x32_bf16 v[26:29], v[188:191], v[204:207], v[26:29]
	v_mfma_f32_16x16x32_bf16 v[18:21], v[180:183], v[212:215], v[18:21]
	v_mfma_f32_16x16x32_bf16 v[10:13], v[188:191], v[212:215], v[10:13]
	v_mfma_f32_16x16x32_bf16 v[6:9], v[180:183], v[220:223], v[6:9]
	v_mfma_f32_16x16x32_bf16 v[2:5], v[188:191], v[220:223], v[2:5]
	v_mfma_f32_16x16x32_bf16 v[50:53], v[184:187], v[200:203], v[50:53]
	v_mfma_f32_16x16x32_bf16 v[42:45], v[192:195], v[200:203], v[42:45]
	v_mfma_f32_16x16x32_bf16 v[34:37], v[184:187], v[208:211], v[34:37]
	v_mfma_f32_16x16x32_bf16 v[26:29], v[192:195], v[208:211], v[26:29]
	v_mfma_f32_16x16x32_bf16 v[18:21], v[184:187], v[216:219], v[18:21]
	v_mfma_f32_16x16x32_bf16 v[10:13], v[192:195], v[216:219], v[10:13]
	v_mfma_f32_16x16x32_bf16 v[6:9], v[184:187], v[224:227], v[6:9]
	v_mfma_f32_16x16x32_bf16 v[2:5], v[192:195], v[224:227], v[2:5]
	s_setprio 0
	s_barrier
	s_add_i32 s54, s54, 2
	s_addk_i32 s52, 0x100
	s_addk_i32 s53, 0x100
	s_cmp_gt_u32 s54, 13
	s_cbranch_scc0 .LBB0_121
	s_and_b64 vcc, exec, s[6:7]
	s_cbranch_vccz .LBB0_126
	s_barrier
	s_cmp_gt_i32 s46, 3
	s_mov_b64 s[16:17], -1
	s_cbranch_scc1 .LBB0_127
